# v79 + P10 epilogue-operand prefetch: bias2/row-sumsq loads issued one unit ahead into free VGPRs (no exposed load latency at unit epilogue)
# speedup vs baseline: 1.0081x; 1.0081x over previous
.LBB0_1288:
	s_add_u32 s8, s12, 0x4c00000
	s_addc_u32 s9, s13, 0
	s_add_u32 s10, s12, 0x20000
	s_addc_u32 s11, s13, 0
	s_add_u32 s46, s12, 0x130000
	s_addc_u32 s47, s13, 0
	s_lshl_b32 s12, s17, 5
	s_and_b32 s54, s12, 0x60
	s_mov_b64 s[12:13], 0x80
	s_add_i32 m0, s34, 0x18000
	v_lshl_add_u64 v[8:9], v[8:9], 0, s[12:13]
	s_lshl_b32 s24, s16, 13
	s_lshl_b32 s17, s54, 7
	s_waitcnt vmcnt(2)
	s_barrier
	global_load_lds_dwordx4 v[8:9], off
	v_lshl_add_u64 v[6:7], v[6:7], 0, s[12:13]
	s_add_i32 m0, s34, 0x1a000
	s_add_i32 s55, s34, 0x8000
	s_add_i32 s56, s34, 0xa000
	global_load_lds_dwordx4 v[6:7], off
	v_lshl_add_u64 v[2:3], v[2:3], 0, s[12:13]
	s_mov_b32 m0, s55
	s_add_u32 s18, s22, 0x40080
	global_load_lds_dwordx4 v[2:3], off
	v_lshl_add_u64 v[2:3], v[4:5], 0, s[12:13]
	s_mov_b32 m0, s56
	s_addc_u32 s19, s23, 0
	global_load_lds_dwordx4 v[2:3], off
	s_add_i32 m0, s34, 0x1c000
	v_lshl_add_u64 v[2:3], s[18:19], 0, v[150:151]
	global_load_lds_dwordx4 v[2:3], off
	v_lshl_add_u64 v[2:3], s[18:19], 0, v[146:147]
	s_add_i32 m0, s34, 0x1e000
	s_cmpk_lt_u32 s15, 0x100
	global_load_lds_dwordx4 v[2:3], off
	v_lshrrev_b32_e32 v3, 1, v10
	v_and_b32_e32 v156, 24, v3
	v_and_b32_e32 v2, 15, v10
	v_lshlrev_b32_e32 v3, 1, v156
	v_lshl_or_b32 v1, s16, 6, v2
	v_lshl_or_b32 v2, v2, 6, v3
	v_lshlrev_b32_e32 v3, 2, v10
	v_and_b32_e32 v3, 32, v3
	v_bitop3_b32 v4, v2, s24, v3 bitop3:0xde
	v_bitop3_b32 v157, v2, s17, v3 bitop3:0xde
	v_lshlrev_b32_e32 v2, 14, v15
	v_and_b32_e32 v2, 0xffff8000, v2
	v_lshl_add_u32 v2, v14, 11, v2
	v_and_b32_e32 v3, 1, v15
	v_lshl_or_b32 v2, v3, 6, v2
	v_lshl_add_u32 v158, v16, 1, v2
	v_lshlrev_b32_e32 v2, 14, v11
	v_and_b32_e32 v2, 0xffff8000, v2
	s_waitcnt vmcnt(6)
	v_lshl_add_u32 v2, v12, 11, v2
	v_and_b32_e32 v3, 1, v11
	s_sext_i32_i8 s52, s14
	s_cselect_b64 s[14:15], -1, 0
	v_lshl_or_b32 v2, v3, 6, v2
	s_add_i32 s57, 0, 0x14000
	v_mov_b32_e32 v159, v155
	v_lshl_add_u32 v160, v13, 1, v2
	v_mov_b32_e32 v161, v155
	v_mov_b64_e32 v[162:163], 0x580
	v_mov_b64_e32 v[164:165], 0x57f
	v_add_u32_e32 v169, s3, v157
	v_add_u32_e32 v171, s57, v157
	v_add_u32_e32 v173, 0, v4
	s_movk_i32 s92, 0x1600
	v_mov_b32_e32 v177, 0x358637bd
	s_mov_b32 s93, 0
	s_barrier
	s_lshr_b32 s98, s4, 5
	s_mul_i32 s98, s98, 0x1600
	s_lshl_b32 s99, s52, 8
	s_add_i32 s98, s98, s99
	s_add_i32 s98, s98, s54
	s_lshl_b32 s98, s98, 2
	s_add_u32 s98, s46, s98
	s_addc_u32 s99, s47, 0
	v_lshlrev_b32_e32 v233, 2, v156
	v_lshl_add_u32 v232, s4, 8, v1
	global_load_dwordx4 v[234:237], v233, s[98:99]
	global_load_dwordx4 v[238:241], v233, s[98:99] offset:16
	global_load_dwordx4 v[242:245], v233, s[98:99] offset:512
	global_load_dwordx4 v[246:249], v233, s[98:99] offset:528
	v_lshlrev_b32_e32 v232, 2, v232
	global_load_dword v250, v232, s[10:11]
	global_load_dword v251, v232, s[10:11] offset:64
	global_load_dword v252, v232, s[10:11] offset:128
	global_load_dword v253, v232, s[10:11] offset:192
	global_load_dword v254, v232, s[10:11] offset:512
	global_load_dword v233, v232, s[10:11] offset:576
	global_load_dword v177, v232, s[10:11] offset:704
	global_load_dword v232, v232, s[10:11] offset:640
	s_branch .LBB0_1291

.LBB0_1297:
	s_lshr_b32 s17, s4, 5
	s_mul_i32 s20, s17, 0x1600
	s_ashr_i32 s21, s20, 31
	s_lshl_b64 s[20:21], s[20:21], 2
	s_add_u32 s17, s46, s20
	s_addc_u32 s19, s47, s21
	s_lshl_b32 s20, s52, 8
	s_ashr_i32 s21, s20, 31
	s_lshl_b64 s[20:21], s[20:21], 2
	s_add_u32 s17, s17, s20
	s_addc_u32 s19, s19, s21
	s_lshl_b32 s20, s54, 2
	v_lshl_add_u32 v166, s4, 8, v1
	s_add_u32 s20, s17, s20
	v_ashrrev_i32_e32 v167, 31, v166
	s_addc_u32 s21, s19, 0
	v_lshlrev_b32_e32 v78, 2, v156
	v_lshl_add_u64 v[174:175], v[166:167], 2, s[10:11]
	v_add_u32_e32 v174, 0x80, v166
	v_ashrrev_i32_e32 v175, 31, v174
	v_lshl_add_u64 v[178:179], v[174:175], 2, s[10:11]
	s_lshl_b32 s20, s52, 7
	s_ashr_i32 s21, s20, 31
	s_lshl_b64 s[20:21], s[20:21], 1
	s_lshl_b32 s4, s54, 1
	s_andn2_b64 vcc, exec, s[40:41]
	s_waitcnt vmcnt(0)
	v_mov_b64_e32 v[94:95], v[234:235]
	v_mov_b64_e32 v[96:97], v[236:237]
	v_mov_b64_e32 v[82:83], v[238:239]
	v_mov_b64_e32 v[84:85], v[240:241]
	v_mov_b64_e32 v[78:79], v[242:243]
	v_mov_b64_e32 v[80:81], v[244:245]
	v_mov_b64_e32 v[70:71], v[246:247]
	v_mov_b64_e32 v[72:73], v[248:249]
	v_mov_b32_e32 v154, v250
	v_mov_b32_e32 v167, v251
	v_mov_b32_e32 v168, v252
	v_mov_b32_e32 v170, v253
	v_mov_b32_e32 v172, v254
	v_mov_b32_e32 v175, v233
	v_mov_b32_e32 v181, v232
	v_mov_b32_e32 v179, v177
	v_mov_b32_e32 v177, 0x358637bd
	v_fmamk_f32 v154, v154, 0x3a800000, v177
	v_fmamk_f32 v167, v167, 0x3a800000, v177
	v_rsq_f32_e32 v182, v167
	v_fmamk_f32 v167, v168, 0x3a800000, v177
	v_rsq_f32_e32 v154, v154
	v_rsq_f32_e32 v180, v167
	v_fmamk_f32 v167, v170, 0x3a800000, v177
	v_rsq_f32_e32 v178, v167
	v_fmamk_f32 v167, v172, 0x3a800000, v177
	v_rsq_f32_e32 v176, v167
	v_fmamk_f32 v167, v175, 0x3a800000, v177
	v_rsq_f32_e32 v172, v167
	v_fmamk_f32 v167, v181, 0x3a800000, v177
	v_rsq_f32_e32 v170, v167
	v_fmamk_f32 v167, v179, 0x3a800000, v177
	s_lshr_b32 s98, s18, 5
	s_mul_i32 s98, s98, 0x1600
	s_lshl_b32 s99, s16, 8
	s_add_i32 s98, s98, s99
	s_add_i32 s98, s98, s54
	s_lshl_b32 s98, s98, 2
	s_add_u32 s98, s46, s98
	s_addc_u32 s99, s47, 0
	v_lshlrev_b32_e32 v233, 2, v156
	v_lshl_add_u32 v232, s18, 8, v1
	global_load_dwordx4 v[234:237], v233, s[98:99]
	global_load_dwordx4 v[238:241], v233, s[98:99] offset:16
	global_load_dwordx4 v[242:245], v233, s[98:99] offset:512
	global_load_dwordx4 v[246:249], v233, s[98:99] offset:528
	v_lshlrev_b32_e32 v232, 2, v232
	global_load_dword v250, v232, s[10:11]
	global_load_dword v251, v232, s[10:11] offset:64
	global_load_dword v252, v232, s[10:11] offset:128
	global_load_dword v253, v232, s[10:11] offset:192
	global_load_dword v254, v232, s[10:11] offset:512
	global_load_dword v233, v232, s[10:11] offset:576
	global_load_dword v177, v232, s[10:11] offset:704
	global_load_dword v232, v232, s[10:11] offset:640
	v_pk_fma_f32 v[142:143], v[142:143], v[154:155], v[94:95] op_sel_hi:[1,0,1]
	v_rsq_f32_e32 v168, v167
	v_mul_f32_e32 v167, 0xbfb8aa3b, v142
	v_exp_f32_e32 v167, v167
	v_pk_fma_f32 v[138:139], v[138:139], v[154:155], v[82:83] op_sel_hi:[1,0,1]
	v_pk_fma_f32 v[134:135], v[134:135], v[154:155], v[78:79] op_sel_hi:[1,0,1]
	v_pk_fma_f32 v[140:141], v[140:141], v[154:155], v[84:85] op_sel_hi:[1,0,1]
	v_add_f32_e32 v167, 1.0, v167
	v_rcp_f32_e32 v184, v167
	v_mul_f32_e32 v167, 0xbfb8aa3b, v138
	v_exp_f32_e32 v167, v167
	v_pk_fma_f32 v[130:131], v[130:131], v[154:155], v[70:71] op_sel_hi:[1,0,1]
	v_pk_fma_f32 v[144:145], v[144:145], v[154:155], v[96:97] op_sel_hi:[1,0,1]
	v_pk_fma_f32 v[136:137], v[136:137], v[154:155], v[80:81] op_sel_hi:[1,0,1]
	v_add_f32_e32 v167, 1.0, v167
	v_rcp_f32_e32 v186, v167
	v_mul_f32_e32 v167, 0xbfb8aa3b, v143
	v_exp_f32_e32 v167, v167
	v_pk_fma_f32 v[132:133], v[132:133], v[154:155], v[72:73] op_sel_hi:[1,0,1]
	v_lshlrev_b32_e32 v154, 1, v156
	v_pk_fma_f32 v[122:123], v[122:123], v[182:183], v[82:83] op_sel_hi:[1,0,1]
	v_add_f32_e32 v167, 1.0, v167
	v_rcp_f32_e32 v185, v167
	v_pk_fma_f32 v[126:127], v[126:127], v[182:183], v[94:95] op_sel_hi:[1,0,1]
	v_pk_fma_f32 v[118:119], v[118:119], v[182:183], v[78:79] op_sel_hi:[1,0,1]
	v_pk_fma_f32 v[124:125], v[124:125], v[182:183], v[84:85] op_sel_hi:[1,0,1]
	v_pk_mul_f32 v[142:143], v[142:143], v[184:185]
	v_pk_fma_f32 v[106:107], v[106:107], v[182:183], v[70:71] op_sel_hi:[1,0,1]
	v_pk_mul_f32 v[134:135], v[134:135], v[142:143]
	v_mul_f32_e32 v142, 0xbfb8aa3b, v139
	v_exp_f32_e32 v142, v142
	v_pk_fma_f32 v[128:129], v[128:129], v[182:183], v[96:97] op_sel_hi:[1,0,1]
	v_pk_fma_f32 v[120:121], v[120:121], v[182:183], v[80:81] op_sel_hi:[1,0,1]
	v_pk_fma_f32 v[108:109], v[108:109], v[182:183], v[72:73] op_sel_hi:[1,0,1]
	v_add_f32_e32 v142, 1.0, v142
	v_rcp_f32_e32 v187, v142
	v_pk_fma_f32 v[110:111], v[110:111], v[180:181], v[82:83] op_sel_hi:[1,0,1]
	v_pk_fma_f32 v[102:103], v[102:103], v[180:181], v[78:79] op_sel_hi:[1,0,1]
	v_pk_fma_f32 v[112:113], v[112:113], v[180:181], v[84:85] op_sel_hi:[1,0,1]
	v_pk_mul_f32 v[138:139], v[138:139], v[186:187]
	v_pk_fma_f32 v[86:87], v[86:87], v[180:181], v[70:71] op_sel_hi:[1,0,1]
	v_pk_mul_f32 v[138:139], v[130:131], v[138:139]
	v_mul_f32_e32 v131, 0xbfb8aa3b, v140
	v_exp_f32_e32 v131, v131
	v_mul_f32_e32 v130, 0xbfb8aa3b, v144
	v_exp_f32_e32 v130, v130
	v_pk_fma_f32 v[104:105], v[104:105], v[180:181], v[80:81] op_sel_hi:[1,0,1]
	v_add_f32_e32 v131, 1.0, v131
	v_rcp_f32_e32 v142, v131
	v_mul_f32_e32 v131, 0xbfb8aa3b, v145
	v_exp_f32_e32 v131, v131
	v_add_f32_e32 v130, 1.0, v130
	v_rcp_f32_e32 v130, v130
	v_pk_fma_f32 v[88:89], v[88:89], v[180:181], v[72:73] op_sel_hi:[1,0,1]
	v_add_f32_e32 v131, 1.0, v131
	v_rcp_f32_e32 v131, v131
	v_pk_fma_f32 v[90:91], v[90:91], v[178:179], v[82:83] op_sel_hi:[1,0,1]
	v_pk_fma_f32 v[74:75], v[74:75], v[178:179], v[78:79] op_sel_hi:[1,0,1]
	v_pk_fma_f32 v[92:93], v[92:93], v[178:179], v[84:85] op_sel_hi:[1,0,1]
	v_pk_mul_f32 v[130:131], v[144:145], v[130:131]
	v_pk_fma_f32 v[66:67], v[66:67], v[178:179], v[70:71] op_sel_hi:[1,0,1]
	v_pk_mul_f32 v[136:137], v[136:137], v[130:131]
	v_mul_f32_e32 v130, 0xbfb8aa3b, v141
	v_exp_f32_e32 v130, v130
	v_pk_fma_f32 v[76:77], v[76:77], v[178:179], v[80:81] op_sel_hi:[1,0,1]
	v_pk_fma_f32 v[68:69], v[68:69], v[178:179], v[72:73] op_sel_hi:[1,0,1]
	v_pk_fma_f32 v[58:59], v[58:59], v[176:177], v[82:83] op_sel_hi:[1,0,1]
	v_add_f32_e32 v130, 1.0, v130
	v_rcp_f32_e32 v143, v130
	v_pk_fma_f32 v[62:63], v[62:63], v[176:177], v[94:95] op_sel_hi:[1,0,1]
	v_pk_fma_f32 v[54:55], v[54:55], v[176:177], v[78:79] op_sel_hi:[1,0,1]
	v_pk_fma_f32 v[60:61], v[60:61], v[176:177], v[84:85] op_sel_hi:[1,0,1]
	v_pk_mul_f32 v[130:131], v[140:141], v[142:143]
	v_pk_fma_f32 v[42:43], v[42:43], v[176:177], v[70:71] op_sel_hi:[1,0,1]
	v_pk_mul_f32 v[140:141], v[132:133], v[130:131]
	v_cvt_pk_bf16_f32 v130, v134, v135
	v_mov_b64_e32 v[134:135], s[8:9]
	v_cvt_pk_bf16_f32 v131, v136, v137
	v_mad_i64_i32 v[136:137], s[22:23], v166, s92, v[134:135]
	v_lshl_add_u64 v[136:137], v[136:137], 0, s[20:21]
	v_lshl_add_u64 v[136:137], v[136:137], 0, s[4:5]
	v_cvt_pk_bf16_f32 v132, v138, v139
	v_cvt_pk_bf16_f32 v133, v140, v141
	v_lshl_add_u64 v[136:137], v[136:137], 0, v[154:155]
	global_store_dwordx4 v[136:137], v[130:133], off
	v_pk_fma_f32 v[64:65], v[64:65], v[176:177], v[96:97] op_sel_hi:[1,0,1]
	v_pk_fma_f32 v[56:57], v[56:57], v[176:177], v[80:81] op_sel_hi:[1,0,1]
	v_mul_f32_e32 v131, 0xbfb8aa3b, v122
	v_exp_f32_e32 v131, v131
	v_mul_f32_e32 v130, 0xbfb8aa3b, v126
	v_exp_f32_e32 v130, v130
	v_pk_fma_f32 v[44:45], v[44:45], v[176:177], v[72:73] op_sel_hi:[1,0,1]
	v_add_f32_e32 v131, 1.0, v131
	v_rcp_f32_e32 v132, v131
	v_mul_f32_e32 v131, 0xbfb8aa3b, v127
	v_exp_f32_e32 v131, v131
	v_add_f32_e32 v130, 1.0, v130
	v_rcp_f32_e32 v130, v130
	v_pk_fma_f32 v[46:47], v[46:47], v[172:173], v[82:83] op_sel_hi:[1,0,1]
	v_add_f32_e32 v131, 1.0, v131
	v_rcp_f32_e32 v131, v131
	v_pk_fma_f32 v[38:39], v[38:39], v[172:173], v[78:79] op_sel_hi:[1,0,1]
	v_pk_fma_f32 v[48:49], v[48:49], v[172:173], v[84:85] op_sel_hi:[1,0,1]
	v_pk_fma_f32 v[26:27], v[26:27], v[172:173], v[70:71] op_sel_hi:[1,0,1]
	v_pk_mul_f32 v[126:127], v[126:127], v[130:131]
	v_pk_fma_f32 v[40:41], v[40:41], v[172:173], v[80:81] op_sel_hi:[1,0,1]
	v_pk_mul_f32 v[118:119], v[118:119], v[126:127]
	v_mul_f32_e32 v126, 0xbfb8aa3b, v123
	v_exp_f32_e32 v126, v126
	v_pk_fma_f32 v[28:29], v[28:29], v[172:173], v[72:73] op_sel_hi:[1,0,1]
	v_pk_fma_f32 v[30:31], v[30:31], v[170:171], v[82:83] op_sel_hi:[1,0,1]
	v_pk_fma_f32 v[22:23], v[22:23], v[170:171], v[78:79] op_sel_hi:[1,0,1]
	v_add_f32_e32 v126, 1.0, v126
	v_rcp_f32_e32 v133, v126
	v_pk_fma_f32 v[32:33], v[32:33], v[170:171], v[84:85] op_sel_hi:[1,0,1]
	v_pk_fma_f32 v[10:11], v[10:11], v[170:171], v[70:71] op_sel_hi:[1,0,1]
	v_pk_fma_f32 v[24:25], v[24:25], v[170:171], v[80:81] op_sel_hi:[1,0,1]
	v_pk_mul_f32 v[122:123], v[122:123], v[132:133]
	v_pk_fma_f32 v[12:13], v[12:13], v[170:171], v[72:73] op_sel_hi:[1,0,1]
	v_pk_mul_f32 v[122:123], v[106:107], v[122:123]
	v_mul_f32_e32 v107, 0xbfb8aa3b, v124
	v_exp_f32_e32 v107, v107
	v_mul_f32_e32 v106, 0xbfb8aa3b, v128
	v_exp_f32_e32 v106, v106
	v_pk_fma_f32 v[14:15], v[14:15], v[168:169], v[82:83] op_sel_hi:[1,0,1]
	v_add_f32_e32 v107, 1.0, v107
	v_rcp_f32_e32 v126, v107
	v_mul_f32_e32 v107, 0xbfb8aa3b, v129
	v_exp_f32_e32 v107, v107
	v_add_f32_e32 v106, 1.0, v106
	v_rcp_f32_e32 v106, v106
	v_pk_fma_f32 v[6:7], v[6:7], v[168:169], v[78:79] op_sel_hi:[1,0,1]
	v_add_f32_e32 v107, 1.0, v107
	v_rcp_f32_e32 v107, v107
	v_pk_fma_f32 v[16:17], v[16:17], v[168:169], v[84:85] op_sel_hi:[1,0,1]
	v_pk_fma_f32 v[2:3], v[2:3], v[168:169], v[70:71] op_sel_hi:[1,0,1]
	v_pk_fma_f32 v[8:9], v[8:9], v[168:169], v[80:81] op_sel_hi:[1,0,1]
	v_pk_mul_f32 v[106:107], v[128:129], v[106:107]
	v_pk_fma_f32 v[4:5], v[4:5], v[168:169], v[72:73] op_sel_hi:[1,0,1]
	v_pk_mul_f32 v[120:121], v[120:121], v[106:107]
	v_mul_f32_e32 v106, 0xbfb8aa3b, v125
	v_exp_f32_e32 v106, v106
	s_nop 0
	v_add_f32_e32 v106, 1.0, v106
	v_rcp_f32_e32 v127, v106
	s_nop 0
	v_pk_mul_f32 v[106:107], v[124:125], v[126:127]
	v_or_b32_e32 v126, 16, v166
	v_pk_mul_f32 v[124:125], v[108:109], v[106:107]
	v_cvt_pk_bf16_f32 v106, v118, v119
	v_mad_i64_i32 v[118:119], s[22:23], v126, s92, v[134:135]
	v_lshl_add_u64 v[118:119], v[118:119], 0, s[20:21]
	v_lshl_add_u64 v[118:119], v[118:119], 0, s[4:5]
	v_cvt_pk_bf16_f32 v107, v120, v121
	v_cvt_pk_bf16_f32 v108, v122, v123
	v_cvt_pk_bf16_f32 v109, v124, v125
	v_lshl_add_u64 v[118:119], v[118:119], 0, v[154:155]
	global_store_dwordx4 v[118:119], v[106:109], off
	s_nop 1
	v_pk_fma_f32 v[108:109], v[114:115], v[180:181], v[94:95] op_sel_hi:[1,0,1]
	v_mul_f32_e32 v115, 0xbfb8aa3b, v110
	v_exp_f32_e32 v115, v115
	v_pk_fma_f32 v[106:107], v[116:117], v[180:181], v[96:97] op_sel_hi:[1,0,1]
	v_mul_f32_e32 v114, 0xbfb8aa3b, v108
	v_exp_f32_e32 v114, v114
	v_add_f32_e32 v115, 1.0, v115
	v_rcp_f32_e32 v116, v115
	v_mul_f32_e32 v115, 0xbfb8aa3b, v109
	v_exp_f32_e32 v115, v115
	v_add_f32_e32 v114, 1.0, v114
	v_rcp_f32_e32 v114, v114
	v_add_f32_e32 v115, 1.0, v115
	v_rcp_f32_e32 v115, v115
	s_nop 0
	v_pk_mul_f32 v[108:109], v[108:109], v[114:115]
	s_nop 0
	v_pk_mul_f32 v[102:103], v[102:103], v[108:109]
	v_mul_f32_e32 v108, 0xbfb8aa3b, v111
	v_exp_f32_e32 v108, v108
	s_nop 0
	v_add_f32_e32 v108, 1.0, v108
	v_rcp_f32_e32 v117, v108
	s_nop 0
	v_pk_mul_f32 v[108:109], v[110:111], v[116:117]
	s_nop 0
	v_pk_mul_f32 v[108:109], v[86:87], v[108:109]
	v_mul_f32_e32 v87, 0xbfb8aa3b, v112
	v_exp_f32_e32 v87, v87
	v_mul_f32_e32 v86, 0xbfb8aa3b, v106
	v_exp_f32_e32 v86, v86
	v_add_f32_e32 v87, 1.0, v87
	v_rcp_f32_e32 v110, v87
	v_mul_f32_e32 v87, 0xbfb8aa3b, v107
	v_exp_f32_e32 v87, v87
	v_add_f32_e32 v86, 1.0, v86
	v_rcp_f32_e32 v86, v86
	v_add_f32_e32 v87, 1.0, v87
	v_rcp_f32_e32 v87, v87
	s_nop 0
	v_pk_mul_f32 v[86:87], v[106:107], v[86:87]
	s_nop 0
	v_pk_mul_f32 v[104:105], v[104:105], v[86:87]
	v_mul_f32_e32 v86, 0xbfb8aa3b, v113
	v_exp_f32_e32 v86, v86
	s_nop 0
	v_add_f32_e32 v86, 1.0, v86
	v_rcp_f32_e32 v111, v86
	s_nop 0
	v_pk_mul_f32 v[86:87], v[112:113], v[110:111]
	v_or_b32_e32 v110, 32, v166
	v_pk_mul_f32 v[106:107], v[88:89], v[86:87]
	v_cvt_pk_bf16_f32 v86, v102, v103
	v_mad_i64_i32 v[102:103], s[22:23], v110, s92, v[134:135]
	v_lshl_add_u64 v[102:103], v[102:103], 0, s[20:21]
	v_lshl_add_u64 v[102:103], v[102:103], 0, s[4:5]
	v_cvt_pk_bf16_f32 v87, v104, v105
	v_cvt_pk_bf16_f32 v88, v108, v109
	v_cvt_pk_bf16_f32 v89, v106, v107
	v_lshl_add_u64 v[102:103], v[102:103], 0, v[154:155]
	global_store_dwordx4 v[102:103], v[86:89], off
	s_nop 1
	v_pk_fma_f32 v[88:89], v[98:99], v[178:179], v[94:95] op_sel_hi:[1,0,1]
	v_mul_f32_e32 v99, 0xbfb8aa3b, v90
	v_exp_f32_e32 v99, v99
	v_pk_fma_f32 v[86:87], v[100:101], v[178:179], v[96:97] op_sel_hi:[1,0,1]
	v_mul_f32_e32 v98, 0xbfb8aa3b, v88
	v_exp_f32_e32 v98, v98
	v_add_f32_e32 v99, 1.0, v99
	v_rcp_f32_e32 v100, v99
	v_mul_f32_e32 v99, 0xbfb8aa3b, v89
	v_exp_f32_e32 v99, v99
	v_add_f32_e32 v98, 1.0, v98
	v_rcp_f32_e32 v98, v98
	v_add_f32_e32 v99, 1.0, v99
	v_rcp_f32_e32 v99, v99
	s_nop 0
	v_pk_mul_f32 v[88:89], v[88:89], v[98:99]
	s_nop 0
	v_pk_mul_f32 v[74:75], v[74:75], v[88:89]
	v_mul_f32_e32 v88, 0xbfb8aa3b, v91
	v_exp_f32_e32 v88, v88
	s_nop 0
	v_add_f32_e32 v88, 1.0, v88
	v_rcp_f32_e32 v101, v88
	s_nop 0
	v_pk_mul_f32 v[88:89], v[90:91], v[100:101]
	s_nop 0
	v_pk_mul_f32 v[88:89], v[66:67], v[88:89]
	v_mul_f32_e32 v67, 0xbfb8aa3b, v92
	v_exp_f32_e32 v67, v67
	v_mul_f32_e32 v66, 0xbfb8aa3b, v86
	v_exp_f32_e32 v66, v66
	v_add_f32_e32 v67, 1.0, v67
	v_rcp_f32_e32 v90, v67
	v_mul_f32_e32 v67, 0xbfb8aa3b, v87
	v_exp_f32_e32 v67, v67
	v_add_f32_e32 v66, 1.0, v66
	v_rcp_f32_e32 v66, v66
	v_add_f32_e32 v67, 1.0, v67
	v_rcp_f32_e32 v67, v67
	s_nop 0
	v_pk_mul_f32 v[66:67], v[86:87], v[66:67]
	s_nop 0
	v_pk_mul_f32 v[76:77], v[76:77], v[66:67]
	v_mul_f32_e32 v66, 0xbfb8aa3b, v93
	v_exp_f32_e32 v66, v66
	s_nop 0
	v_add_f32_e32 v66, 1.0, v66
	v_rcp_f32_e32 v91, v66
	s_nop 0
	v_pk_mul_f32 v[66:67], v[92:93], v[90:91]
	v_or_b32_e32 v90, 48, v166
	v_pk_mul_f32 v[86:87], v[68:69], v[66:67]
	v_cvt_pk_bf16_f32 v66, v74, v75
	v_mad_i64_i32 v[74:75], s[22:23], v90, s92, v[134:135]
	v_lshl_add_u64 v[74:75], v[74:75], 0, s[20:21]
	v_lshl_add_u64 v[74:75], v[74:75], 0, s[4:5]
	v_cvt_pk_bf16_f32 v67, v76, v77
	v_cvt_pk_bf16_f32 v68, v88, v89
	v_cvt_pk_bf16_f32 v69, v86, v87
	v_lshl_add_u64 v[74:75], v[74:75], 0, v[154:155]
	global_store_dwordx4 v[74:75], v[66:69], off
	s_nop 1
	v_mul_f32_e32 v67, 0xbfb8aa3b, v58
	v_exp_f32_e32 v67, v67
	v_mul_f32_e32 v66, 0xbfb8aa3b, v62
	v_exp_f32_e32 v66, v66
	v_add_f32_e32 v67, 1.0, v67
	v_rcp_f32_e32 v68, v67
	v_mul_f32_e32 v67, 0xbfb8aa3b, v63
	v_exp_f32_e32 v67, v67
	v_add_f32_e32 v66, 1.0, v66
	v_rcp_f32_e32 v66, v66
	v_add_f32_e32 v67, 1.0, v67
	v_rcp_f32_e32 v67, v67
	s_nop 0
	v_pk_mul_f32 v[62:63], v[62:63], v[66:67]
	s_nop 0
	v_pk_mul_f32 v[54:55], v[54:55], v[62:63]
	v_mul_f32_e32 v62, 0xbfb8aa3b, v59
	v_exp_f32_e32 v62, v62
	s_nop 0
	v_add_f32_e32 v62, 1.0, v62
	v_rcp_f32_e32 v69, v62
	s_nop 0
	v_pk_mul_f32 v[58:59], v[58:59], v[68:69]
	s_nop 0
	v_pk_mul_f32 v[58:59], v[42:43], v[58:59]
	v_mul_f32_e32 v43, 0xbfb8aa3b, v60
	v_exp_f32_e32 v43, v43
	v_mul_f32_e32 v42, 0xbfb8aa3b, v64
	v_exp_f32_e32 v42, v42
	v_add_f32_e32 v43, 1.0, v43
	v_rcp_f32_e32 v62, v43
	v_mul_f32_e32 v43, 0xbfb8aa3b, v65
	v_exp_f32_e32 v43, v43
	v_add_f32_e32 v42, 1.0, v42
	v_rcp_f32_e32 v42, v42
	v_add_f32_e32 v43, 1.0, v43
	v_rcp_f32_e32 v43, v43
	s_nop 0
	v_pk_mul_f32 v[42:43], v[64:65], v[42:43]
	s_nop 0
	v_pk_mul_f32 v[56:57], v[56:57], v[42:43]
	v_mul_f32_e32 v42, 0xbfb8aa3b, v61
	v_exp_f32_e32 v42, v42
	s_nop 0
	v_add_f32_e32 v42, 1.0, v42
	v_rcp_f32_e32 v63, v42
	s_nop 0
	v_pk_mul_f32 v[42:43], v[60:61], v[62:63]
	s_nop 0
	v_pk_mul_f32 v[60:61], v[44:45], v[42:43]
	v_cvt_pk_bf16_f32 v42, v54, v55
	v_mad_i64_i32 v[54:55], s[22:23], v174, s92, v[134:135]
	v_lshl_add_u64 v[54:55], v[54:55], 0, s[20:21]
	v_lshl_add_u64 v[54:55], v[54:55], 0, s[4:5]
	v_cvt_pk_bf16_f32 v43, v56, v57
	v_cvt_pk_bf16_f32 v44, v58, v59
	v_cvt_pk_bf16_f32 v45, v60, v61
	v_lshl_add_u64 v[54:55], v[54:55], 0, v[154:155]
	global_store_dwordx4 v[54:55], v[42:45], off
	s_nop 1
	v_pk_fma_f32 v[44:45], v[50:51], v[172:173], v[94:95] op_sel_hi:[1,0,1]
	v_mul_f32_e32 v51, 0xbfb8aa3b, v46
	v_exp_f32_e32 v51, v51
	v_pk_fma_f32 v[42:43], v[52:53], v[172:173], v[96:97] op_sel_hi:[1,0,1]
	v_mul_f32_e32 v50, 0xbfb8aa3b, v44
	v_exp_f32_e32 v50, v50
	v_add_f32_e32 v51, 1.0, v51
	v_rcp_f32_e32 v52, v51
	v_mul_f32_e32 v51, 0xbfb8aa3b, v45
	v_exp_f32_e32 v51, v51
	v_add_f32_e32 v50, 1.0, v50
	v_rcp_f32_e32 v50, v50
	v_add_f32_e32 v51, 1.0, v51
	v_rcp_f32_e32 v51, v51
	s_nop 0
	v_pk_mul_f32 v[44:45], v[44:45], v[50:51]
	s_nop 0
	v_pk_mul_f32 v[38:39], v[38:39], v[44:45]
	v_mul_f32_e32 v44, 0xbfb8aa3b, v47
	v_exp_f32_e32 v44, v44
	s_nop 0
	v_add_f32_e32 v44, 1.0, v44
	v_rcp_f32_e32 v53, v44
	s_nop 0
	v_pk_mul_f32 v[44:45], v[46:47], v[52:53]
	s_nop 0
	v_pk_mul_f32 v[44:45], v[26:27], v[44:45]
	v_mul_f32_e32 v27, 0xbfb8aa3b, v48
	v_exp_f32_e32 v27, v27
	v_mul_f32_e32 v26, 0xbfb8aa3b, v42
	v_exp_f32_e32 v26, v26
	v_add_f32_e32 v27, 1.0, v27
	v_rcp_f32_e32 v46, v27
	v_mul_f32_e32 v27, 0xbfb8aa3b, v43
	v_exp_f32_e32 v27, v27
	v_add_f32_e32 v26, 1.0, v26
	v_rcp_f32_e32 v26, v26
	v_add_f32_e32 v27, 1.0, v27
	v_rcp_f32_e32 v27, v27
	s_nop 0
	v_pk_mul_f32 v[26:27], v[42:43], v[26:27]
	s_nop 0
	v_pk_mul_f32 v[40:41], v[40:41], v[26:27]
	v_mul_f32_e32 v26, 0xbfb8aa3b, v49
	v_exp_f32_e32 v26, v26
	s_nop 0
	v_add_f32_e32 v26, 1.0, v26
	v_rcp_f32_e32 v47, v26
	s_nop 0
	v_pk_mul_f32 v[26:27], v[48:49], v[46:47]
	v_add_u32_e32 v46, 0x90, v166
	v_pk_mul_f32 v[42:43], v[28:29], v[26:27]
	v_cvt_pk_bf16_f32 v26, v38, v39
	v_mad_i64_i32 v[38:39], s[22:23], v46, s92, v[134:135]
	v_lshl_add_u64 v[38:39], v[38:39], 0, s[20:21]
	v_lshl_add_u64 v[38:39], v[38:39], 0, s[4:5]
	v_cvt_pk_bf16_f32 v27, v40, v41
	v_cvt_pk_bf16_f32 v28, v44, v45
	v_cvt_pk_bf16_f32 v29, v42, v43
	v_lshl_add_u64 v[38:39], v[38:39], 0, v[154:155]
	global_store_dwordx4 v[38:39], v[26:29], off
	s_nop 1
	v_pk_fma_f32 v[28:29], v[34:35], v[170:171], v[94:95] op_sel_hi:[1,0,1]
	v_mul_f32_e32 v35, 0xbfb8aa3b, v30
	v_exp_f32_e32 v35, v35
	v_pk_fma_f32 v[26:27], v[36:37], v[170:171], v[96:97] op_sel_hi:[1,0,1]
	v_mul_f32_e32 v34, 0xbfb8aa3b, v28
	v_exp_f32_e32 v34, v34
	v_add_f32_e32 v35, 1.0, v35
	v_rcp_f32_e32 v36, v35
	v_mul_f32_e32 v35, 0xbfb8aa3b, v29
	v_exp_f32_e32 v35, v35
	v_add_f32_e32 v34, 1.0, v34
	v_rcp_f32_e32 v34, v34
	v_add_f32_e32 v35, 1.0, v35
	v_rcp_f32_e32 v35, v35
	s_nop 0
	v_pk_mul_f32 v[28:29], v[28:29], v[34:35]
	s_nop 0
	v_pk_mul_f32 v[22:23], v[22:23], v[28:29]
	v_mul_f32_e32 v28, 0xbfb8aa3b, v31
	v_exp_f32_e32 v28, v28
	s_nop 0
	v_add_f32_e32 v28, 1.0, v28
	v_rcp_f32_e32 v37, v28
	s_nop 0
	v_pk_mul_f32 v[28:29], v[30:31], v[36:37]
	s_nop 0
	v_pk_mul_f32 v[28:29], v[10:11], v[28:29]
	v_mul_f32_e32 v11, 0xbfb8aa3b, v32
	v_exp_f32_e32 v11, v11
	v_mul_f32_e32 v10, 0xbfb8aa3b, v26
	v_exp_f32_e32 v10, v10
	v_add_f32_e32 v11, 1.0, v11
	v_rcp_f32_e32 v30, v11
	v_mul_f32_e32 v11, 0xbfb8aa3b, v27
	v_exp_f32_e32 v11, v11
	v_add_f32_e32 v10, 1.0, v10
	v_rcp_f32_e32 v10, v10
	v_add_f32_e32 v11, 1.0, v11
	v_rcp_f32_e32 v11, v11
	s_nop 0
	v_pk_mul_f32 v[10:11], v[26:27], v[10:11]
	s_nop 0
	v_pk_mul_f32 v[24:25], v[24:25], v[10:11]
	v_mul_f32_e32 v10, 0xbfb8aa3b, v33
	v_exp_f32_e32 v10, v10
	s_nop 0
	v_add_f32_e32 v10, 1.0, v10
	v_rcp_f32_e32 v31, v10
	s_nop 0
	v_pk_mul_f32 v[10:11], v[32:33], v[30:31]
	v_add_u32_e32 v30, 0xa0, v166
	v_pk_mul_f32 v[26:27], v[12:13], v[10:11]
	v_cvt_pk_bf16_f32 v10, v22, v23
	v_mad_i64_i32 v[22:23], s[22:23], v30, s92, v[134:135]
	v_lshl_add_u64 v[22:23], v[22:23], 0, s[20:21]
	v_lshl_add_u64 v[22:23], v[22:23], 0, s[4:5]
	v_cvt_pk_bf16_f32 v11, v24, v25
	v_cvt_pk_bf16_f32 v12, v28, v29
	v_cvt_pk_bf16_f32 v13, v26, v27
	v_lshl_add_u64 v[22:23], v[22:23], 0, v[154:155]
	global_store_dwordx4 v[22:23], v[10:13], off
	s_nop 1
	v_pk_fma_f32 v[12:13], v[18:19], v[168:169], v[94:95] op_sel_hi:[1,0,1]
	v_mul_f32_e32 v19, 0xbfb8aa3b, v14
	v_exp_f32_e32 v19, v19
	v_pk_fma_f32 v[10:11], v[20:21], v[168:169], v[96:97] op_sel_hi:[1,0,1]
	v_mul_f32_e32 v18, 0xbfb8aa3b, v12
	v_exp_f32_e32 v18, v18
	v_add_f32_e32 v19, 1.0, v19
	v_rcp_f32_e32 v20, v19
	v_mul_f32_e32 v19, 0xbfb8aa3b, v13
	v_exp_f32_e32 v19, v19
	v_add_f32_e32 v18, 1.0, v18
	v_rcp_f32_e32 v18, v18
	v_add_f32_e32 v19, 1.0, v19
	v_rcp_f32_e32 v19, v19
	s_nop 0
	v_pk_mul_f32 v[12:13], v[12:13], v[18:19]
	s_nop 0
	v_pk_mul_f32 v[6:7], v[6:7], v[12:13]
	v_mul_f32_e32 v12, 0xbfb8aa3b, v15
	v_exp_f32_e32 v12, v12
	s_nop 0
	v_add_f32_e32 v12, 1.0, v12
	v_rcp_f32_e32 v21, v12
	s_nop 0
	v_pk_mul_f32 v[12:13], v[14:15], v[20:21]
	s_nop 0
	v_pk_mul_f32 v[12:13], v[2:3], v[12:13]
	v_mul_f32_e32 v3, 0xbfb8aa3b, v16
	v_exp_f32_e32 v3, v3
	v_mul_f32_e32 v2, 0xbfb8aa3b, v10
	v_exp_f32_e32 v2, v2
	v_add_f32_e32 v3, 1.0, v3
	v_rcp_f32_e32 v14, v3
	v_mul_f32_e32 v3, 0xbfb8aa3b, v11
	v_exp_f32_e32 v3, v3
	v_add_f32_e32 v2, 1.0, v2
	v_rcp_f32_e32 v2, v2
	v_add_f32_e32 v3, 1.0, v3
	v_rcp_f32_e32 v3, v3
	s_nop 0
	v_pk_mul_f32 v[2:3], v[10:11], v[2:3]
	s_nop 0
	v_pk_mul_f32 v[8:9], v[8:9], v[2:3]
	v_mul_f32_e32 v2, 0xbfb8aa3b, v17
	v_exp_f32_e32 v2, v2
	s_nop 0
	v_add_f32_e32 v2, 1.0, v2
	v_rcp_f32_e32 v15, v2
	s_nop 0
	v_pk_mul_f32 v[2:3], v[16:17], v[14:15]
	v_add_u32_e32 v14, 0xb0, v166
	v_pk_mul_f32 v[10:11], v[4:5], v[2:3]
	v_cvt_pk_bf16_f32 v2, v6, v7
	v_mad_i64_i32 v[6:7], s[22:23], v14, s92, v[134:135]
	v_lshl_add_u64 v[6:7], v[6:7], 0, s[20:21]
	v_lshl_add_u64 v[6:7], v[6:7], 0, s[4:5]
	v_cvt_pk_bf16_f32 v3, v8, v9
	v_cvt_pk_bf16_f32 v4, v12, v13
	v_cvt_pk_bf16_f32 v5, v10, v11
	v_lshl_add_u64 v[6:7], v[6:7], 0, v[154:155]
	s_mov_b64 s[20:21], -1
	global_store_dwordx4 v[6:7], v[2:5], off
	s_cbranch_vccnz .LBB0_1290
	s_andn2_b64 vcc, exec, s[6:7]
	s_cbranch_vccnz .LBB0_1289
	s_barrier
	s_branch .LBB0_1289

	.amdhsa_kernel _Z8mega_fwd4Args
		.amdhsa_group_segment_fixed_size 0
		.amdhsa_private_segment_fixed_size 0
		.amdhsa_kernarg_size 488
		.amdhsa_user_sgpr_count 2
		.amdhsa_user_sgpr_dispatch_ptr 0
		.amdhsa_user_sgpr_queue_ptr 0
		.amdhsa_user_sgpr_kernarg_segment_ptr 1
		.amdhsa_user_sgpr_dispatch_id 0
		.amdhsa_user_sgpr_kernarg_preload_length 0
		.amdhsa_user_sgpr_kernarg_preload_offset 0
		.amdhsa_user_sgpr_private_segment_size 0
		.amdhsa_uses_dynamic_stack 0
		.amdhsa_enable_private_segment 0
		.amdhsa_system_sgpr_workgroup_id_x 1
		.amdhsa_system_sgpr_workgroup_id_y 0
		.amdhsa_system_sgpr_workgroup_id_z 0
		.amdhsa_system_sgpr_workgroup_info 0
		.amdhsa_system_vgpr_workitem_id 0
		.amdhsa_next_free_vgpr 256
		.amdhsa_next_free_sgpr 102
		.amdhsa_accum_offset 256
		.amdhsa_reserve_vcc 1
		.amdhsa_float_round_mode_32 0
		.amdhsa_float_round_mode_16_64 0
		.amdhsa_float_denorm_mode_32 3
		.amdhsa_float_denorm_mode_16_64 3
		.amdhsa_dx10_clamp 1
		.amdhsa_ieee_mode 1
		.amdhsa_fp16_overflow 0
		.amdhsa_tg_split 0
		.amdhsa_exception_fp_ieee_invalid_op 0
		.amdhsa_exception_fp_denorm_src 0
		.amdhsa_exception_fp_ieee_div_zero 0
		.amdhsa_exception_fp_ieee_overflow 0
		.amdhsa_exception_fp_ieee_underflow 0
		.amdhsa_exception_fp_ieee_inexact 0
		.amdhsa_exception_int_div_zero 0
	.end_amdhsa_kernel

amdhsa.kernels:
  - .agpr_count:     0
    .args:
      - .offset:         0
        .size:           232
        .value_kind:     by_value
      - .offset:         232
        .size:           4
        .value_kind:     hidden_block_count_x
      - .offset:         236
        .size:           4
        .value_kind:     hidden_block_count_y
      - .offset:         240
        .size:           4
        .value_kind:     hidden_block_count_z
      - .offset:         244
        .size:           2
        .value_kind:     hidden_group_size_x
      - .offset:         246
        .size:           2
        .value_kind:     hidden_group_size_y
      - .offset:         248
        .size:           2
        .value_kind:     hidden_group_size_z
      - .offset:         250
        .size:           2
        .value_kind:     hidden_remainder_x
      - .offset:         252
        .size:           2
        .value_kind:     hidden_remainder_y
      - .offset:         254
        .size:           2
        .value_kind:     hidden_remainder_z
      - .offset:         272
        .size:           8
        .value_kind:     hidden_global_offset_x
      - .offset:         280
        .size:           8
        .value_kind:     hidden_global_offset_y
      - .offset:         288
        .size:           8
        .value_kind:     hidden_global_offset_z
      - .offset:         296
        .size:           2
        .value_kind:     hidden_grid_dims
      - .offset:         352
        .size:           4
        .value_kind:     hidden_dynamic_lds_size
    .group_segment_fixed_size: 0
    .kernarg_segment_align: 8
    .kernarg_segment_size: 488
    .language:       OpenCL C
    .language_version:
      - 2
      - 0
    .max_flat_workgroup_size: 512
    .name:           _Z8mega_fwd4Args
    .private_segment_fixed_size: 0
    .sgpr_count:     108
    .sgpr_spill_count: 68
    .symbol:         _Z8mega_fwd4Args.kd
    .uniform_work_group_size: 1
    .uses_dynamic_stack: false
    .vgpr_count:     256
    .vgpr_spill_count: 0
    .wavefront_size: 64
